# v12 + MA: remaining pieces of a row requested together with its first piece (unused prefetch loads)
# speedup vs baseline: 1.0104x; 1.0011x over previous
; #define GAS __attribute__((address_space(1)))
; #define LAS __attribute__((address_space(3)))
; __device__ __forceinline__ void phase_fa(const Params& p, Frame& F, int l, const float* xraw) {
;     ...
;             for (int i = 0; i < 16; ++i) { const int q = F.tid + 512 * i, row = q >> 7, c128 = q & 127;
;                 const v4u v = *(const GAS v4u*)(H + ((size_t)b * S + 128 * row + s2) * D + c128 * 8);
;                 *(LAS v4u*)(F.lds + (c128 >> 4) * 16384 + off_b(row, c128 & 15)) = v; }
.LBB0_234:
	v_mov_b32_e32 v190, v90
	v_and_b32_e32 v192, 0xffffff80, v190
	v_ashrrev_i32_e32 v193, 31, v192
	v_lshl_add_u64 v[192:193], s[4:5], 0, v[192:193]
	v_lshlrev_b64 v[192:193], 11, v[192:193]
	v_lshl_add_u64 v[192:193], v[68:69], 0, v[192:193]
	global_load_dwordx4 v[0:3], v[192:193], off
	v_ashrrev_i32_e32 v191, 7, v190
	v_lshlrev_b32_e32 v194, 2, v191
	v_lshlrev_b32_e32 v195, 8, v191
	v_and_b32_e32 v194, 12, v194
	v_bfe_u32 v191, v191, 2, 2
	v_bitop3_b32 v191, v194, v91, v191 bitop3:0x36
	v_lshlrev_b32_e32 v191, 4, v191
	v_add3_u32 v146, v111, v191, v195
	v_add_u32_e32 v190, 0x200, v90
	v_and_b32_e32 v192, 0xffffff80, v190
	v_ashrrev_i32_e32 v193, 31, v192
	v_lshl_add_u64 v[192:193], s[4:5], 0, v[192:193]
	v_lshlrev_b64 v[192:193], 11, v[192:193]
	v_lshl_add_u64 v[192:193], v[68:69], 0, v[192:193]
	global_load_dwordx4 v[4:7], v[192:193], off
	v_ashrrev_i32_e32 v191, 7, v190
	v_lshlrev_b32_e32 v194, 2, v191
	v_lshlrev_b32_e32 v195, 8, v191
	v_and_b32_e32 v194, 12, v194
	v_bfe_u32 v191, v191, 2, 2
	v_bitop3_b32 v191, v194, v91, v191 bitop3:0x36
	v_lshlrev_b32_e32 v191, 4, v191
	v_add3_u32 v147, v111, v191, v195
	v_add_u32_e32 v190, 0x400, v90
	v_and_b32_e32 v192, 0xffffff80, v190
	v_ashrrev_i32_e32 v193, 31, v192
	v_lshl_add_u64 v[192:193], s[4:5], 0, v[192:193]
	v_lshlrev_b64 v[192:193], 11, v[192:193]
	v_lshl_add_u64 v[192:193], v[68:69], 0, v[192:193]
	global_load_dwordx4 v[8:11], v[192:193], off
	v_ashrrev_i32_e32 v191, 7, v190
	v_lshlrev_b32_e32 v194, 2, v191
	v_lshlrev_b32_e32 v195, 8, v191
	v_and_b32_e32 v194, 12, v194
	v_bfe_u32 v191, v191, 2, 2
	v_bitop3_b32 v191, v194, v91, v191 bitop3:0x36
	v_lshlrev_b32_e32 v191, 4, v191
	v_add3_u32 v148, v111, v191, v195
	v_add_u32_e32 v190, 0x600, v90
	v_and_b32_e32 v192, 0xffffff80, v190
	v_ashrrev_i32_e32 v193, 31, v192
	v_lshl_add_u64 v[192:193], s[4:5], 0, v[192:193]
	v_lshlrev_b64 v[192:193], 11, v[192:193]
	v_lshl_add_u64 v[192:193], v[68:69], 0, v[192:193]
	global_load_dwordx4 v[12:15], v[192:193], off
	v_ashrrev_i32_e32 v191, 7, v190
	v_lshlrev_b32_e32 v194, 2, v191
	v_lshlrev_b32_e32 v195, 8, v191
	v_and_b32_e32 v194, 12, v194
	v_bfe_u32 v191, v191, 2, 2
	v_bitop3_b32 v191, v194, v91, v191 bitop3:0x36
	v_lshlrev_b32_e32 v191, 4, v191
	v_add3_u32 v149, v111, v191, v195
	v_add_u32_e32 v190, 0x800, v90
	v_and_b32_e32 v192, 0xffffff80, v190
	v_ashrrev_i32_e32 v193, 31, v192
	v_lshl_add_u64 v[192:193], s[4:5], 0, v[192:193]
	v_lshlrev_b64 v[192:193], 11, v[192:193]
	v_lshl_add_u64 v[192:193], v[68:69], 0, v[192:193]
	global_load_dwordx4 v[16:19], v[192:193], off
	v_ashrrev_i32_e32 v191, 7, v190
	v_lshlrev_b32_e32 v194, 2, v191
	v_lshlrev_b32_e32 v195, 8, v191
	v_and_b32_e32 v194, 12, v194
	v_bfe_u32 v191, v191, 2, 2
	v_bitop3_b32 v191, v194, v91, v191 bitop3:0x36
	v_lshlrev_b32_e32 v191, 4, v191
	v_add3_u32 v150, v111, v191, v195
	v_add_u32_e32 v190, 0xa00, v90
	v_and_b32_e32 v192, 0xffffff80, v190
	v_ashrrev_i32_e32 v193, 31, v192
	v_lshl_add_u64 v[192:193], s[4:5], 0, v[192:193]
	v_lshlrev_b64 v[192:193], 11, v[192:193]
	v_lshl_add_u64 v[192:193], v[68:69], 0, v[192:193]
	global_load_dwordx4 v[20:23], v[192:193], off
	v_ashrrev_i32_e32 v191, 7, v190
	v_lshlrev_b32_e32 v194, 2, v191
	v_lshlrev_b32_e32 v195, 8, v191
	v_and_b32_e32 v194, 12, v194
	v_bfe_u32 v191, v191, 2, 2
	v_bitop3_b32 v191, v194, v91, v191 bitop3:0x36
	v_lshlrev_b32_e32 v191, 4, v191
	v_add3_u32 v151, v111, v191, v195
	v_add_u32_e32 v190, 0xc00, v90
	v_and_b32_e32 v192, 0xffffff80, v190
	v_ashrrev_i32_e32 v193, 31, v192
	v_lshl_add_u64 v[192:193], s[4:5], 0, v[192:193]
	v_lshlrev_b64 v[192:193], 11, v[192:193]
	v_lshl_add_u64 v[192:193], v[68:69], 0, v[192:193]
	global_load_dwordx4 v[24:27], v[192:193], off
	v_ashrrev_i32_e32 v191, 7, v190
	v_lshlrev_b32_e32 v194, 2, v191
	v_lshlrev_b32_e32 v195, 8, v191
	v_and_b32_e32 v194, 12, v194
	v_bfe_u32 v191, v191, 2, 2
	v_bitop3_b32 v191, v194, v91, v191 bitop3:0x36
	v_lshlrev_b32_e32 v191, 4, v191
	v_add3_u32 v170, v111, v191, v195
	v_add_u32_e32 v190, 0xe00, v90
	v_and_b32_e32 v192, 0xffffff80, v190
	v_ashrrev_i32_e32 v193, 31, v192
	v_lshl_add_u64 v[192:193], s[4:5], 0, v[192:193]
	v_lshlrev_b64 v[192:193], 11, v[192:193]
	v_lshl_add_u64 v[192:193], v[68:69], 0, v[192:193]
	global_load_dwordx4 v[28:31], v[192:193], off
	v_ashrrev_i32_e32 v191, 7, v190
	v_lshlrev_b32_e32 v194, 2, v191
	v_lshlrev_b32_e32 v195, 8, v191
	v_and_b32_e32 v194, 12, v194
	v_bfe_u32 v191, v191, 2, 2
	v_bitop3_b32 v191, v194, v91, v191 bitop3:0x36
	v_lshlrev_b32_e32 v191, 4, v191
	v_add3_u32 v171, v111, v191, v195
	v_add_u32_e32 v190, 0x1000, v90
	v_and_b32_e32 v192, 0xffffff80, v190
	v_ashrrev_i32_e32 v193, 31, v192
	v_lshl_add_u64 v[192:193], s[4:5], 0, v[192:193]
	v_lshlrev_b64 v[192:193], 11, v[192:193]
	v_lshl_add_u64 v[192:193], v[68:69], 0, v[192:193]
	global_load_dwordx4 v[32:35], v[192:193], off
	v_ashrrev_i32_e32 v191, 7, v190
	v_lshlrev_b32_e32 v194, 2, v191
	v_lshlrev_b32_e32 v195, 8, v191
	v_and_b32_e32 v194, 12, v194
; #define GAS __attribute__((address_space(1)))
; #define LAS __attribute__((address_space(3)))
; __device__ __forceinline__ void phase_fa(const Params& p, Frame& F, int l, const float* xraw) {
;     ...
;             for (int i = 0; i < 16; ++i) { const int q = F.tid + 512 * i, row = q >> 7, c128 = q & 127;
;                 const v4u v = *(const GAS v4u*)(H + ((size_t)b * S + 128 * row + s2) * D + c128 * 8);
;                 *(LAS v4u*)(F.lds + (c128 >> 4) * 16384 + off_b(row, c128 & 15)) = v; }
	v_bfe_u32 v191, v191, 2, 2
	v_bitop3_b32 v191, v194, v91, v191 bitop3:0x36
	v_lshlrev_b32_e32 v191, 4, v191
	v_add3_u32 v172, v111, v191, v195
	v_add_u32_e32 v190, 0x1200, v90
	v_and_b32_e32 v192, 0xffffff80, v190
	v_ashrrev_i32_e32 v193, 31, v192
	v_lshl_add_u64 v[192:193], s[4:5], 0, v[192:193]
	v_lshlrev_b64 v[192:193], 11, v[192:193]
	v_lshl_add_u64 v[192:193], v[68:69], 0, v[192:193]
	global_load_dwordx4 v[36:39], v[192:193], off
	v_ashrrev_i32_e32 v191, 7, v190
	v_lshlrev_b32_e32 v194, 2, v191
	v_lshlrev_b32_e32 v195, 8, v191
	v_and_b32_e32 v194, 12, v194
	v_bfe_u32 v191, v191, 2, 2
	v_bitop3_b32 v191, v194, v91, v191 bitop3:0x36
	v_lshlrev_b32_e32 v191, 4, v191
	v_add3_u32 v173, v111, v191, v195
	v_add_u32_e32 v190, 0x1400, v90
	v_and_b32_e32 v192, 0xffffff80, v190
	v_ashrrev_i32_e32 v193, 31, v192
	v_lshl_add_u64 v[192:193], s[4:5], 0, v[192:193]
	v_lshlrev_b64 v[192:193], 11, v[192:193]
	v_lshl_add_u64 v[192:193], v[68:69], 0, v[192:193]
	global_load_dwordx4 v[40:43], v[192:193], off
	v_ashrrev_i32_e32 v191, 7, v190
	v_lshlrev_b32_e32 v194, 2, v191
	v_lshlrev_b32_e32 v195, 8, v191
	v_and_b32_e32 v194, 12, v194
	v_bfe_u32 v191, v191, 2, 2
	v_bitop3_b32 v191, v194, v91, v191 bitop3:0x36
	v_lshlrev_b32_e32 v191, 4, v191
	v_add3_u32 v174, v111, v191, v195
	v_add_u32_e32 v190, 0x1600, v90
	v_and_b32_e32 v192, 0xffffff80, v190
	v_ashrrev_i32_e32 v193, 31, v192
	v_lshl_add_u64 v[192:193], s[4:5], 0, v[192:193]
	v_lshlrev_b64 v[192:193], 11, v[192:193]
	v_lshl_add_u64 v[192:193], v[68:69], 0, v[192:193]
	global_load_dwordx4 v[44:47], v[192:193], off
	v_ashrrev_i32_e32 v191, 7, v190
	v_lshlrev_b32_e32 v194, 2, v191
	v_lshlrev_b32_e32 v195, 8, v191
	v_and_b32_e32 v194, 12, v194
	v_bfe_u32 v191, v191, 2, 2
	v_bitop3_b32 v191, v194, v91, v191 bitop3:0x36
	v_lshlrev_b32_e32 v191, 4, v191
	v_add3_u32 v175, v111, v191, v195
	v_add_u32_e32 v190, 0x1800, v90
	v_and_b32_e32 v192, 0xffffff80, v190
	v_ashrrev_i32_e32 v193, 31, v192
	v_lshl_add_u64 v[192:193], s[4:5], 0, v[192:193]
	v_lshlrev_b64 v[192:193], 11, v[192:193]
	v_lshl_add_u64 v[192:193], v[68:69], 0, v[192:193]
	global_load_dwordx4 v[72:75], v[192:193], off
	v_ashrrev_i32_e32 v191, 7, v190
	v_lshlrev_b32_e32 v194, 2, v191
	v_lshlrev_b32_e32 v195, 8, v191
	v_and_b32_e32 v194, 12, v194
	v_bfe_u32 v191, v191, 2, 2
	v_bitop3_b32 v191, v194, v91, v191 bitop3:0x36
	v_lshlrev_b32_e32 v191, 4, v191
	v_add3_u32 v176, v111, v191, v195
	v_add_u32_e32 v190, 0x1a00, v90
	v_and_b32_e32 v192, 0xffffff80, v190
	v_ashrrev_i32_e32 v193, 31, v192
	v_lshl_add_u64 v[192:193], s[4:5], 0, v[192:193]
	v_lshlrev_b64 v[192:193], 11, v[192:193]
	v_lshl_add_u64 v[192:193], v[68:69], 0, v[192:193]
	global_load_dwordx4 v[76:79], v[192:193], off
	v_ashrrev_i32_e32 v191, 7, v190
	v_lshlrev_b32_e32 v194, 2, v191
	v_lshlrev_b32_e32 v195, 8, v191
	v_and_b32_e32 v194, 12, v194
	v_bfe_u32 v191, v191, 2, 2
	v_bitop3_b32 v191, v194, v91, v191 bitop3:0x36
	v_lshlrev_b32_e32 v191, 4, v191
	v_add3_u32 v177, v111, v191, v195
	v_add_u32_e32 v190, 0x1c00, v90
	v_and_b32_e32 v192, 0xffffff80, v190
	v_ashrrev_i32_e32 v193, 31, v192
	v_lshl_add_u64 v[192:193], s[4:5], 0, v[192:193]
	v_lshlrev_b64 v[192:193], 11, v[192:193]
	v_lshl_add_u64 v[192:193], v[68:69], 0, v[192:193]
	global_load_dwordx4 v[80:83], v[192:193], off
	v_ashrrev_i32_e32 v191, 7, v190
	v_lshlrev_b32_e32 v194, 2, v191
	v_lshlrev_b32_e32 v195, 8, v191
	v_and_b32_e32 v194, 12, v194
	v_bfe_u32 v191, v191, 2, 2
	v_bitop3_b32 v191, v194, v91, v191 bitop3:0x36
	v_lshlrev_b32_e32 v191, 4, v191
	v_add3_u32 v188, v111, v191, v195
	v_add_u32_e32 v190, 0x1e00, v90
	v_and_b32_e32 v192, 0xffffff80, v190
	v_ashrrev_i32_e32 v193, 31, v192
	v_lshl_add_u64 v[192:193], s[4:5], 0, v[192:193]
	v_lshlrev_b64 v[192:193], 11, v[192:193]
	v_lshl_add_u64 v[192:193], v[68:69], 0, v[192:193]
	global_load_dwordx4 v[84:87], v[192:193], off
	v_ashrrev_i32_e32 v191, 7, v190
	v_lshlrev_b32_e32 v194, 2, v191
	v_lshlrev_b32_e32 v195, 8, v191
	v_and_b32_e32 v194, 12, v194
	v_bfe_u32 v191, v191, 2, 2
	v_bitop3_b32 v191, v194, v91, v191 bitop3:0x36
	v_lshlrev_b32_e32 v191, 4, v191
	v_add3_u32 v189, v111, v191, v195
	s_waitcnt vmcnt(15)
	ds_write_b128 v146, v[0:3]
	s_waitcnt vmcnt(14)
	ds_write_b128 v147, v[4:7]
	s_waitcnt vmcnt(13)
	ds_write_b128 v148, v[8:11]
	s_waitcnt vmcnt(12)
	ds_write_b128 v149, v[12:15]
	s_waitcnt vmcnt(11)
	ds_write_b128 v150, v[16:19]
	s_waitcnt vmcnt(10)
	ds_write_b128 v151, v[20:23]
	s_waitcnt vmcnt(9)
	ds_write_b128 v170, v[24:27]
	s_waitcnt vmcnt(8)
	ds_write_b128 v171, v[28:31]
	s_waitcnt vmcnt(7)
	ds_write_b128 v172, v[32:35]
	s_waitcnt vmcnt(6)
	ds_write_b128 v173, v[36:39]
	s_waitcnt vmcnt(5)
	ds_write_b128 v174, v[40:43]
	s_waitcnt vmcnt(4)
	ds_write_b128 v175, v[44:47]
	s_waitcnt vmcnt(3)
	ds_write_b128 v176, v[72:75]
	s_waitcnt vmcnt(2)
	ds_write_b128 v177, v[76:79]
	s_waitcnt vmcnt(1)
	ds_write_b128 v188, v[80:83]
	s_waitcnt vmcnt(0)
	ds_write_b128 v189, v[84:87]
	s_movk_i32 s6, 0x2000
	v_mov_b64_e32 v[32:33], s[18:19]

; #define GAS __attribute__((address_space(1)))
; __device__ __forceinline__ void phase_ma(const Params& p, Frame& F, int l, const bool fd, const float* xin32) {
;     ...
;             for (int j = 0; j < 4; ++j) { if (!fd) { const v2u xw = *(const GAS v2u*)(xb + (size_t)row * D + 256 * j + 4 * F.lane); h[r][j] = (f32x4){bf_lo(xw.x), bf_hi(xw.x), bf_lo(xw.y), bf_hi(xw.y)}; } ss += (h[r][j].x * h[r][j].x + h[r][j].y * h[r][j].y) + (h[r][j].z * h[r][j].z + h[r][j].w * h[r][j].w); }
.LBB0_615:
	s_waitcnt lgkmcnt(0)
	global_load_dwordx2 v[188:189], v[32:33], off offset:512
	global_load_dwordx2 v[190:191], v[32:33], off offset:1024
	global_load_dwordx2 v[192:193], v[32:33], off offset:1536
	global_load_dwordx2 v[34:35], v[32:33], off
	s_waitcnt vmcnt(0)
	v_lshlrev_b32_e32 v78, 16, v34
	v_and_b32_e32 v79, 0xffff0000, v34
	v_lshlrev_b32_e32 v112, 16, v35
	v_and_b32_e32 v113, 0xffff0000, v35
	s_and_b64 vcc, exec, s[48:49]
	s_cbranch_vccz .LBB0_666

; #define GAS __attribute__((address_space(1)))
; __device__ __forceinline__ void phase_ma(const Params& p, Frame& F, int l, const bool fd, const float* xin32) {
;     ...
;                     if (special) y = *(const f32x4*)(y4096 + b * 1024 + cc); else { const v2u pw = *(const GAS v2u*)(P + cc), qw = *(const GAS v2u*)(P + 1024 + cc);
;                         y.x = bf_lo(pw.x) + sg * bf_lo(qw.x); y.y = bf_hi(pw.x) + sg * bf_hi(qw.x); y.z = bf_lo(pw.y) + sg * bf_lo(qw.y); y.w = bf_hi(pw.y) + sg * bf_hi(qw.y); }
.LBB0_632:
	s_xor_b64 s[14:15], s[8:9], -1
	s_add_i32 s8, s18, s34
	s_ashr_i32 s9, s8, 31
	s_lshl_b64 s[8:9], s[8:9], 12
	s_add_u32 s8, s27, s8
	s_addc_u32 s9, s28, s9
	s_mov_b64 s[16:17], -1
	s_and_b64 vcc, exec, s[14:15]
	v_lshl_add_u64 v[68:69], v[66:67], 1, s[8:9]
	s_cbranch_vccz .LBB0_634
	s_waitcnt lgkmcnt(0)
	global_load_dwordx2 v[188:189], v[68:69], off offset:512
	global_load_dwordx2 v[190:191], v[68:69], off offset:1024
	global_load_dwordx2 v[192:193], v[68:69], off offset:1536
	global_load_dwordx2 v[194:195], v[68:69], off offset:2560
	global_load_dwordx2 v[196:197], v[68:69], off offset:3072
	global_load_dwordx2 v[198:199], v[68:69], off offset:3584
	global_load_dwordx2 v[34:35], v[68:69], off
	global_load_dwordx2 v[36:37], v[68:69], off offset:2048
	s_mov_b64 s[16:17], 0
	s_waitcnt vmcnt(0)
	v_lshlrev_b32_e32 v32, 16, v34
	v_and_b32_e32 v33, 0xffff0000, v34
	s_waitcnt vmcnt(0)
	v_lshlrev_b32_e32 v38, 16, v36
	v_and_b32_e32 v39, 0xffff0000, v36
	v_lshlrev_b32_e32 v34, 16, v35
	v_and_b32_e32 v35, 0xffff0000, v35
	v_lshlrev_b32_e32 v36, 16, v37
	v_and_b32_e32 v37, 0xffff0000, v37
	v_pk_fma_f32 v[32:33], s[12:13], v[38:39], v[32:33] op_sel_hi:[0,1,1]
	v_pk_fma_f32 v[34:35], s[12:13], v[36:37], v[34:35] op_sel_hi:[0,1,1]

; #define GAS __attribute__((address_space(1)))
; __device__ __forceinline__ void phase_ma(const Params& p, Frame& F, int l, const bool fd, const float* xin32) {
;     ...
;                     f32x4 xo; if (xin32) xo = *(const GAS f32x4*)(xin32 + (size_t)row * D + cc); else { const v2u xw = *(const GAS v2u*)(xb + (size_t)row * D + cc); xo = (f32x4){bf_lo(xw.x), bf_hi(xw.x), bf_lo(xw.y), bf_hi(xw.y)}; }
.LBB0_636:
	s_ashr_i32 s3, s2, 31
	s_lshl_b64 s[8:9], s[2:3], 11
	s_add_u32 s16, s6, s8
	s_addc_u32 s17, s7, s9
	s_lshl_b64 s[2:3], s[2:3], 12
	v_lshl_add_u64 v[36:37], v[64:65], 0, s[2:3]
	v_lshl_add_u64 v[70:71], v[66:67], 2, v[36:37]
	s_and_saveexec_b64 s[2:3], s[36:37]
	s_xor_b64 s[2:3], exec, s[2:3]
	s_cbranch_execz .LBB0_638
	global_load_dwordx4 v[212:215], v[70:71], off offset:1024
	global_load_dwordx4 v[216:219], v[70:71], off offset:2048
	global_load_dwordx4 v[220:223], v[70:71], off offset:3072
	global_load_dwordx4 v[36:39], v[70:71], off
.LBB0_638:
	s_or_saveexec_b64 s[2:3], s[2:3]
	v_lshl_add_u64 v[84:85], v[66:67], 1, s[16:17]
	s_xor_b64 exec, exec, s[2:3]
	s_cbranch_execz .LBB0_640
	global_load_dwordx2 v[200:201], v[84:85], off offset:512
	global_load_dwordx2 v[202:203], v[84:85], off offset:1024
	global_load_dwordx2 v[204:205], v[84:85], off offset:1536
	global_load_dwordx2 v[38:39], v[84:85], off
	s_waitcnt vmcnt(0)
	v_lshlrev_b32_e32 v36, 16, v38
	v_and_b32_e32 v37, 0xffff0000, v38
	v_lshlrev_b32_e32 v38, 16, v39
	v_and_b32_e32 v39, 0xffff0000, v39

; #define GAS __attribute__((address_space(1)))
; __device__ __forceinline__ void phase_ma(const Params& p, Frame& F, int l, const bool fd, const float* xin32) {
;     ...
;             for (int j = 0; j < 4; ++j) { if (!fd) { const v2u xw = *(const GAS v2u*)(xb + (size_t)row * D + 256 * j + 4 * F.lane); h[r][j] = (f32x4){bf_lo(xw.x), bf_hi(xw.x), bf_lo(xw.y), bf_hi(xw.y)}; } ss += (h[r][j].x * h[r][j].x + h[r][j].y * h[r][j].y) + (h[r][j].z * h[r][j].z + h[r][j].w * h[r][j].w); }
.LBB0_672:
	s_waitcnt lgkmcnt(0)
	global_load_dwordx2 v[188:189], v[32:33], off offset:512
	global_load_dwordx2 v[190:191], v[32:33], off offset:1024
	global_load_dwordx2 v[192:193], v[32:33], off offset:1536
	global_load_dwordx2 v[34:35], v[32:33], off
	s_waitcnt vmcnt(0)
	v_lshlrev_b32_e32 v76, 16, v34
	v_and_b32_e32 v77, 0xffff0000, v34
	v_lshlrev_b32_e32 v110, 16, v35
	v_and_b32_e32 v111, 0xffff0000, v35
	s_and_b64 vcc, exec, s[48:49]
	s_cbranch_vccz .LBB0_723

; #define GAS __attribute__((address_space(1)))
; __device__ __forceinline__ void phase_ma(const Params& p, Frame& F, int l, const bool fd, const float* xin32) {
;     ...
;                     if (special) y = *(const f32x4*)(y4096 + b * 1024 + cc); else { const v2u pw = *(const GAS v2u*)(P + cc), qw = *(const GAS v2u*)(P + 1024 + cc);
;                         y.x = bf_lo(pw.x) + sg * bf_lo(qw.x); y.y = bf_hi(pw.x) + sg * bf_hi(qw.x); y.z = bf_lo(pw.y) + sg * bf_lo(qw.y); y.w = bf_hi(pw.y) + sg * bf_hi(qw.y); }
.LBB0_689:
	s_add_i32 s12, s20, s34
	s_ashr_i32 s13, s12, 31
	s_lshl_b64 s[12:13], s[12:13], 12
	s_add_u32 s12, s27, s12
	s_addc_u32 s13, s28, s13
	s_mov_b64 s[2:3], -1
	s_and_b64 vcc, exec, s[18:19]
	v_lshl_add_u64 v[72:73], v[66:67], 1, s[12:13]
	s_cbranch_vccnz .LBB0_691
	s_waitcnt lgkmcnt(0)
	global_load_dwordx2 v[188:189], v[72:73], off offset:512
	global_load_dwordx2 v[190:191], v[72:73], off offset:1024
	global_load_dwordx2 v[192:193], v[72:73], off offset:1536
	global_load_dwordx2 v[194:195], v[72:73], off offset:2560
	global_load_dwordx2 v[196:197], v[72:73], off offset:3072
	global_load_dwordx2 v[198:199], v[72:73], off offset:3584
	global_load_dwordx2 v[34:35], v[72:73], off
	global_load_dwordx2 v[36:37], v[72:73], off offset:2048
	s_mov_b64 s[2:3], 0
	s_waitcnt vmcnt(0)
	v_lshlrev_b32_e32 v32, 16, v34
	v_and_b32_e32 v33, 0xffff0000, v34
	s_waitcnt vmcnt(0)
	v_lshlrev_b32_e32 v38, 16, v36
	v_and_b32_e32 v39, 0xffff0000, v36
	v_lshlrev_b32_e32 v34, 16, v35
	v_and_b32_e32 v35, 0xffff0000, v35
	v_lshlrev_b32_e32 v36, 16, v37
	v_and_b32_e32 v37, 0xffff0000, v37
	v_pk_fma_f32 v[32:33], s[14:15], v[38:39], v[32:33] op_sel_hi:[0,1,1]
	v_pk_fma_f32 v[34:35], s[14:15], v[36:37], v[34:35] op_sel_hi:[0,1,1]

; #define GAS __attribute__((address_space(1)))
; __device__ __forceinline__ void phase_ma(const Params& p, Frame& F, int l, const bool fd, const float* xin32) {
;     ...
;                     f32x4 xo; if (xin32) xo = *(const GAS f32x4*)(xin32 + (size_t)row * D + cc); else { const v2u xw = *(const GAS v2u*)(xb + (size_t)row * D + cc); xo = (f32x4){bf_lo(xw.x), bf_hi(xw.x), bf_lo(xw.y), bf_hi(xw.y)}; }
.LBB0_693:
	s_ashr_i32 s17, s16, 31
	s_lshl_b64 s[12:13], s[16:17], 11
	s_add_u32 s20, s6, s12
	s_addc_u32 s21, s7, s13
	s_lshl_b64 s[2:3], s[16:17], 12
	v_lshl_add_u64 v[36:37], v[64:65], 0, s[2:3]
	v_lshl_add_u64 v[74:75], v[66:67], 2, v[36:37]
	s_and_saveexec_b64 s[2:3], s[36:37]
	s_xor_b64 s[2:3], exec, s[2:3]
	s_cbranch_execz .LBB0_695
	global_load_dwordx4 v[212:215], v[74:75], off offset:1024
	global_load_dwordx4 v[216:219], v[74:75], off offset:2048
	global_load_dwordx4 v[220:223], v[74:75], off offset:3072
	global_load_dwordx4 v[36:39], v[74:75], off
.LBB0_695:
	s_or_saveexec_b64 s[2:3], s[2:3]
	v_lshl_add_u64 v[94:95], v[66:67], 1, s[20:21]
	s_xor_b64 exec, exec, s[2:3]
	s_cbranch_execz .LBB0_697
	global_load_dwordx2 v[200:201], v[94:95], off offset:512
	global_load_dwordx2 v[202:203], v[94:95], off offset:1024
	global_load_dwordx2 v[204:205], v[94:95], off offset:1536
	global_load_dwordx2 v[38:39], v[94:95], off
	s_waitcnt vmcnt(0)
	v_lshlrev_b32_e32 v36, 16, v38
	v_and_b32_e32 v37, 0xffff0000, v38
	v_lshlrev_b32_e32 v38, 16, v39
	v_and_b32_e32 v39, 0xffff0000, v39

; #define GAS __attribute__((address_space(1)))
; __device__ __forceinline__ void phase_ma(const Params& p, Frame& F, int l, const bool fd, const float* xin32) {
;     ...
;             for (int j = 0; j < 4; ++j) { if (!fd) { const v2u xw = *(const GAS v2u*)(xb + (size_t)row * D + 256 * j + 4 * F.lane); h[r][j] = (f32x4){bf_lo(xw.x), bf_hi(xw.x), bf_lo(xw.y), bf_hi(xw.y)}; } ss += (h[r][j].x * h[r][j].x + h[r][j].y * h[r][j].y) + (h[r][j].z * h[r][j].z + h[r][j].w * h[r][j].w); }
.LBB0_729:
	s_waitcnt lgkmcnt(0)
	global_load_dwordx2 v[188:189], v[32:33], off offset:512
	global_load_dwordx2 v[190:191], v[32:33], off offset:1024
	global_load_dwordx2 v[192:193], v[32:33], off offset:1536
	global_load_dwordx2 v[34:35], v[32:33], off
	s_waitcnt vmcnt(0)
	v_lshlrev_b32_e32 v86, 16, v34
	v_and_b32_e32 v87, 0xffff0000, v34
	v_lshlrev_b32_e32 v116, 16, v35
	v_and_b32_e32 v117, 0xffff0000, v35
	s_and_b64 vcc, exec, s[48:49]
	s_cbranch_vccz .LBB0_780

; #define GAS __attribute__((address_space(1)))
; __device__ __forceinline__ void phase_ma(const Params& p, Frame& F, int l, const bool fd, const float* xin32) {
;     ...
;                     if (special) y = *(const f32x4*)(y4096 + b * 1024 + cc); else { const v2u pw = *(const GAS v2u*)(P + cc), qw = *(const GAS v2u*)(P + 1024 + cc);
;                         y.x = bf_lo(pw.x) + sg * bf_lo(qw.x); y.y = bf_hi(pw.x) + sg * bf_hi(qw.x); y.z = bf_lo(pw.y) + sg * bf_lo(qw.y); y.w = bf_hi(pw.y) + sg * bf_hi(qw.y); }
.LBB0_746:
	s_add_i32 s14, s22, s34
	s_ashr_i32 s15, s14, 31
	s_lshl_b64 s[14:15], s[14:15], 12
	s_add_u32 s14, s27, s14
	s_addc_u32 s15, s28, s15
	s_mov_b64 s[2:3], -1
	s_and_b64 vcc, exec, s[20:21]
	v_lshl_add_u64 v[80:81], v[66:67], 1, s[14:15]
	s_cbranch_vccnz .LBB0_748
	s_waitcnt lgkmcnt(0)
	global_load_dwordx2 v[188:189], v[80:81], off offset:512
	global_load_dwordx2 v[190:191], v[80:81], off offset:1024
	global_load_dwordx2 v[192:193], v[80:81], off offset:1536
	global_load_dwordx2 v[194:195], v[80:81], off offset:2560
	global_load_dwordx2 v[196:197], v[80:81], off offset:3072
	global_load_dwordx2 v[198:199], v[80:81], off offset:3584
	global_load_dwordx2 v[34:35], v[80:81], off
	global_load_dwordx2 v[36:37], v[80:81], off offset:2048
	s_mov_b64 s[2:3], 0
	s_waitcnt vmcnt(0)
	v_lshlrev_b32_e32 v32, 16, v34
	v_and_b32_e32 v33, 0xffff0000, v34
	s_waitcnt vmcnt(0)
	v_lshlrev_b32_e32 v38, 16, v36
	v_and_b32_e32 v39, 0xffff0000, v36
	v_lshlrev_b32_e32 v34, 16, v35
	v_and_b32_e32 v35, 0xffff0000, v35
	v_lshlrev_b32_e32 v36, 16, v37
	v_and_b32_e32 v37, 0xffff0000, v37
	v_pk_fma_f32 v[32:33], s[16:17], v[38:39], v[32:33] op_sel_hi:[0,1,1]
	v_pk_fma_f32 v[34:35], s[16:17], v[36:37], v[34:35] op_sel_hi:[0,1,1]

; #define GAS __attribute__((address_space(1)))
; __device__ __forceinline__ void phase_ma(const Params& p, Frame& F, int l, const bool fd, const float* xin32) {
;     ...
;                     f32x4 xo; if (xin32) xo = *(const GAS f32x4*)(xin32 + (size_t)row * D + cc); else { const v2u xw = *(const GAS v2u*)(xb + (size_t)row * D + cc); xo = (f32x4){bf_lo(xw.x), bf_hi(xw.x), bf_lo(xw.y), bf_hi(xw.y)}; }
.LBB0_750:
	s_ashr_i32 s19, s18, 31
	s_lshl_b64 s[14:15], s[18:19], 11
	s_add_u32 s22, s6, s14
	s_addc_u32 s23, s7, s15
	s_lshl_b64 s[2:3], s[18:19], 12
	v_lshl_add_u64 v[36:37], v[64:65], 0, s[2:3]
	v_lshl_add_u64 v[82:83], v[66:67], 2, v[36:37]
	s_and_saveexec_b64 s[2:3], s[36:37]
	s_xor_b64 s[2:3], exec, s[2:3]
	s_cbranch_execz .LBB0_752
	global_load_dwordx4 v[212:215], v[82:83], off offset:1024
	global_load_dwordx4 v[216:219], v[82:83], off offset:2048
	global_load_dwordx4 v[220:223], v[82:83], off offset:3072
	global_load_dwordx4 v[36:39], v[82:83], off
.LBB0_752:
	s_or_saveexec_b64 s[2:3], s[2:3]
	v_lshl_add_u64 v[114:115], v[66:67], 1, s[22:23]
	s_xor_b64 exec, exec, s[2:3]
	s_cbranch_execz .LBB0_754
	global_load_dwordx2 v[200:201], v[114:115], off offset:512
	global_load_dwordx2 v[202:203], v[114:115], off offset:1024
	global_load_dwordx2 v[204:205], v[114:115], off offset:1536
	global_load_dwordx2 v[38:39], v[114:115], off
	s_waitcnt vmcnt(0)
	v_lshlrev_b32_e32 v36, 16, v38
	v_and_b32_e32 v37, 0xffff0000, v38
	v_lshlrev_b32_e32 v38, 16, v39
	v_and_b32_e32 v39, 0xffff0000, v39

; #define GAS __attribute__((address_space(1)))
; __device__ __forceinline__ void phase_ma(const Params& p, Frame& F, int l, const bool fd, const float* xin32) {
;     ...
;             for (int j = 0; j < 4; ++j) { if (!fd) { const v2u xw = *(const GAS v2u*)(xb + (size_t)row * D + 256 * j + 4 * F.lane); h[r][j] = (f32x4){bf_lo(xw.x), bf_hi(xw.x), bf_lo(xw.y), bf_hi(xw.y)}; } ss += (h[r][j].x * h[r][j].x + h[r][j].y * h[r][j].y) + (h[r][j].z * h[r][j].z + h[r][j].w * h[r][j].w); }
.LBB0_786:
	s_waitcnt lgkmcnt(0)
	global_load_dwordx2 v[188:189], v[32:33], off offset:512
	global_load_dwordx2 v[190:191], v[32:33], off offset:1024
	global_load_dwordx2 v[192:193], v[32:33], off offset:1536
	global_load_dwordx2 v[34:35], v[32:33], off
	s_waitcnt vmcnt(0)
	v_lshlrev_b32_e32 v98, 16, v34
	v_and_b32_e32 v99, 0xffff0000, v34
	v_lshlrev_b32_e32 v120, 16, v35
	v_and_b32_e32 v121, 0xffff0000, v35
	s_and_b64 vcc, exec, s[48:49]
	s_cbranch_vccz .LBB0_837

; #define GAS __attribute__((address_space(1)))
; __device__ __forceinline__ void phase_ma(const Params& p, Frame& F, int l, const bool fd, const float* xin32) {
;     ...
;                     if (special) y = *(const f32x4*)(y4096 + b * 1024 + cc); else { const v2u pw = *(const GAS v2u*)(P + cc), qw = *(const GAS v2u*)(P + 1024 + cc);
;                         y.x = bf_lo(pw.x) + sg * bf_lo(qw.x); y.y = bf_hi(pw.x) + sg * bf_hi(qw.x); y.z = bf_lo(pw.y) + sg * bf_lo(qw.y); y.w = bf_hi(pw.y) + sg * bf_hi(qw.y); }
.LBB0_803:
	s_add_i32 s16, s24, s34
	s_ashr_i32 s17, s16, 31
	s_lshl_b64 s[16:17], s[16:17], 12
	s_add_u32 s16, s27, s16
	s_addc_u32 s17, s28, s17
	s_mov_b64 s[2:3], -1
	s_and_b64 vcc, exec, s[22:23]
	v_lshl_add_u64 v[88:89], v[66:67], 1, s[16:17]
	s_cbranch_vccnz .LBB0_805
	s_waitcnt lgkmcnt(0)
	global_load_dwordx2 v[188:189], v[88:89], off offset:512
	global_load_dwordx2 v[190:191], v[88:89], off offset:1024
	global_load_dwordx2 v[192:193], v[88:89], off offset:1536
	global_load_dwordx2 v[194:195], v[88:89], off offset:2560
	global_load_dwordx2 v[196:197], v[88:89], off offset:3072
	global_load_dwordx2 v[198:199], v[88:89], off offset:3584
	global_load_dwordx2 v[34:35], v[88:89], off
	global_load_dwordx2 v[36:37], v[88:89], off offset:2048
	s_mov_b64 s[2:3], 0
	s_waitcnt vmcnt(0)
	v_lshlrev_b32_e32 v32, 16, v34
	v_and_b32_e32 v33, 0xffff0000, v34
	s_waitcnt vmcnt(0)
	v_lshlrev_b32_e32 v38, 16, v36
	v_and_b32_e32 v39, 0xffff0000, v36
	v_lshlrev_b32_e32 v34, 16, v35
	v_and_b32_e32 v35, 0xffff0000, v35
	v_lshlrev_b32_e32 v36, 16, v37
	v_and_b32_e32 v37, 0xffff0000, v37
	v_pk_fma_f32 v[32:33], s[18:19], v[38:39], v[32:33] op_sel_hi:[0,1,1]
	v_pk_fma_f32 v[34:35], s[18:19], v[36:37], v[34:35] op_sel_hi:[0,1,1]

; #define GAS __attribute__((address_space(1)))
; __device__ __forceinline__ void phase_ma(const Params& p, Frame& F, int l, const bool fd, const float* xin32) {
;     ...
;                     f32x4 xo; if (xin32) xo = *(const GAS f32x4*)(xin32 + (size_t)row * D + cc); else { const v2u xw = *(const GAS v2u*)(xb + (size_t)row * D + cc); xo = (f32x4){bf_lo(xw.x), bf_hi(xw.x), bf_lo(xw.y), bf_hi(xw.y)}; }
.LBB0_807:
	s_ashr_i32 s21, s20, 31
	s_lshl_b64 s[16:17], s[20:21], 11
	s_add_u32 s24, s6, s16
	s_addc_u32 s25, s7, s17
	s_lshl_b64 s[2:3], s[20:21], 12
	v_lshl_add_u64 v[36:37], v[64:65], 0, s[2:3]
	v_lshl_add_u64 v[90:91], v[66:67], 2, v[36:37]
	s_and_saveexec_b64 s[2:3], s[36:37]
	s_xor_b64 s[2:3], exec, s[2:3]
	s_cbranch_execz .LBB0_809
	global_load_dwordx4 v[212:215], v[90:91], off offset:1024
	global_load_dwordx4 v[216:219], v[90:91], off offset:2048
	global_load_dwordx4 v[220:223], v[90:91], off offset:3072
	global_load_dwordx4 v[36:39], v[90:91], off
.LBB0_809:
	s_or_saveexec_b64 s[2:3], s[2:3]
	v_lshl_add_u64 v[122:123], v[66:67], 1, s[24:25]
	s_xor_b64 exec, exec, s[2:3]
	s_cbranch_execz .LBB0_811
	global_load_dwordx2 v[200:201], v[122:123], off offset:512
	global_load_dwordx2 v[202:203], v[122:123], off offset:1024
	global_load_dwordx2 v[204:205], v[122:123], off offset:1536
	global_load_dwordx2 v[38:39], v[122:123], off
	s_waitcnt vmcnt(0)
	v_lshlrev_b32_e32 v36, 16, v38
	v_and_b32_e32 v37, 0xffff0000, v38
	v_lshlrev_b32_e32 v38, 16, v39
	v_and_b32_e32 v39, 0xffff0000, v39
